# residual-add GEMM epilogues: issue the 8 in-place residual loads of each token together (counted vmcnt) instead of 32 serialized load-wait-store round trips per tile
# speedup vs baseline: 1.0061x; 1.0034x over previous
; __device__ __forceinline__ uint2 pack4(float a, float b, float c, float d) { uint2 r; r.x = pk2(a, b); r.y = pk2(c, d); return r; }
;   __device__ __forceinline__ void operator()(EPI_ARGS) {
;     _Pragma("unroll") for (int bj = 0; bj < 2; ++bj) _Pragma("unroll") for (int n = 0; n < 2; ++n) {
;       int t = S_TOK(bj, n); float ss = 0.f;
;       u16* xbp = xb + (long)t * DM;
;       _Pragma("unroll") for (int ai = 0; ai < 2; ++ai) _Pragma("unroll") for (int m = 0; m < 4; ++m) {
;         int f = S_FEAT(ai, m); f32x4 a = acc[ai][bj][m][n];
;         uint2 xv = *(const uint2*)(xbp + f);
;         float v0 = __uint_as_float(xv.x << 16) + a[0], v1 = __uint_as_float(xv.x & 0xffff0000u) + a[1];
;         float v2 = __uint_as_float(xv.y << 16) + a[2], v3 = __uint_as_float(xv.y & 0xffff0000u) + a[3];
;         *(uint2*)(xbp + f) = pack4(v0, v1, v2, v3);
;         ss += v0 * v0 + v1 * v1 + v2 * v2 + v3 * v3;
;       }
;       ss += sx<16>(ss, fq * 16 + fr); ss += sx<32>(ss, fq * 16 + fr);
;       if (fq == 0) part[(long)t * 8 + (fc0 >> 8) * 2 + wr] = ss;
;     }
.LBB0_1932:
	s_mov_b32 s0, -1
	s_ashr_i32 s10, s19, 7
	v_mbcnt_lo_u32_b32 v32, s0, 0
	v_mbcnt_hi_u32_b32 v32, s0, v32
	v_or_b32_e32 v32, s97, v32
	s_ashr_i32 s11, s10, 31
	v_ashrrev_i32_e32 v130, 8, v32
	v_and_b32_e32 v131, 15, v32
	v_bfe_u32 v133, v32, 4, 2
	v_lshrrev_b32_e32 v32, 1, v32
	v_and_b32_e32 v32, 0x60, v32
	v_add3_u32 v134, v131, s20, v32
	v_lshl_add_u32 v32, v130, 6, s19
	v_ashrrev_i32_e32 v135, 31, v134
	v_lshl_or_b32 v132, v133, 2, v32
	v_lshlrev_b64 v[136:137], 11, v[134:135]
	v_lshlrev_b32_e32 v32, 6, v133
	v_cmp_eq_u32_e32 vcc, 0, v133
	v_lshl_add_u64 v[136:137], s[6:7], 0, v[136:137]
	v_ashrrev_i32_e32 v133, 31, v132
	v_lshl_add_u64 v[136:137], v[132:133], 1, v[136:137]
	global_load_dwordx2 v[138:139], v[136:137], off
	global_load_dwordx2 v[186:187], v[136:137], off offset:32
	global_load_dwordx2 v[188:189], v[136:137], off offset:64
	global_load_dwordx2 v[190:191], v[136:137], off offset:96
	global_load_dwordx2 v[192:193], v[136:137], off offset:256
	global_load_dwordx2 v[194:195], v[136:137], off offset:288
	global_load_dwordx2 v[196:197], v[136:137], off offset:320
	global_load_dwordx2 v[198:199], v[136:137], off offset:352
	v_lshlrev_b32_e32 v131, 2, v131
	v_bitop3_b32 v32, v32, s57, v131 bitop3:0x36
	v_ashrrev_i32_e32 v131, 31, v130
	s_waitcnt vmcnt(7)
	v_lshlrev_b32_e32 v140, 16, v138
	v_and_b32_e32 v141, 0xffff0000, v138
	v_lshlrev_b32_e32 v138, 16, v139
	v_and_b32_e32 v139, 0xffff0000, v139
	v_pk_add_f32 v[126:127], v[126:127], v[140:141]
	v_pk_add_f32 v[138:139], v[128:129], v[138:139]
	v_cvt_pk_bf16_f32 v128, v126, v127
	v_cvt_pk_bf16_f32 v129, v138, v139
	global_store_dwordx2 v[136:137], v[128:129], off
	v_pk_mul_f32 v[128:129], v[126:127], v[126:127]
	v_pk_mul_f32 v[126:127], v[138:139], v[138:139]
	s_waitcnt vmcnt(7)
	v_lshlrev_b32_e32 v140, 16, v186
	v_and_b32_e32 v141, 0xffff0000, v186
	v_lshlrev_b32_e32 v138, 16, v187
	v_and_b32_e32 v139, 0xffff0000, v187
	v_pk_add_f32 v[122:123], v[122:123], v[140:141]
	v_pk_add_f32 v[138:139], v[124:125], v[138:139]
	v_cvt_pk_bf16_f32 v124, v122, v123
	v_cvt_pk_bf16_f32 v125, v138, v139
	global_store_dwordx2 v[136:137], v[124:125], off offset:32
	v_pk_mul_f32 v[124:125], v[122:123], v[122:123]
	v_pk_mul_f32 v[122:123], v[138:139], v[138:139]
	v_add_f32_e32 v124, v124, v125
	v_add_f32_e32 v122, v124, v122
	v_add_f32_e32 v122, v123, v122
	v_add_f32_e32 v123, v128, v129
	v_add_f32_e32 v123, v123, v126
	v_add_f32_e32 v123, v127, v123
	v_add_f32_e32 v122, v123, v122
	s_waitcnt vmcnt(7)
	v_lshlrev_b32_e32 v140, 16, v188
	v_and_b32_e32 v141, 0xffff0000, v188
	v_lshlrev_b32_e32 v138, 16, v189
	v_and_b32_e32 v139, 0xffff0000, v189
	v_pk_add_f32 v[118:119], v[118:119], v[140:141]
	v_pk_add_f32 v[138:139], v[120:121], v[138:139]
	v_cvt_pk_bf16_f32 v120, v118, v119
	v_cvt_pk_bf16_f32 v121, v138, v139
	global_store_dwordx2 v[136:137], v[120:121], off offset:64
	v_pk_mul_f32 v[120:121], v[118:119], v[118:119]
	v_pk_mul_f32 v[118:119], v[138:139], v[138:139]
	v_add_f32_e32 v120, v120, v121
	v_add_f32_e32 v118, v120, v118
	v_add_f32_e32 v118, v119, v118
	v_add_f32_e32 v118, v122, v118
	s_waitcnt vmcnt(7)
	v_lshlrev_b32_e32 v140, 16, v190
	v_and_b32_e32 v141, 0xffff0000, v190
	v_lshlrev_b32_e32 v138, 16, v191
	v_and_b32_e32 v139, 0xffff0000, v191
	v_pk_add_f32 v[114:115], v[114:115], v[140:141]
	v_pk_add_f32 v[138:139], v[116:117], v[138:139]
	v_cvt_pk_bf16_f32 v116, v114, v115
	v_cvt_pk_bf16_f32 v117, v138, v139
	global_store_dwordx2 v[136:137], v[116:117], off offset:96
	v_pk_mul_f32 v[116:117], v[114:115], v[114:115]
	v_pk_mul_f32 v[114:115], v[138:139], v[138:139]
	v_add_f32_e32 v116, v116, v117
	v_add_f32_e32 v114, v116, v114
	v_add_f32_e32 v114, v115, v114
	v_add_f32_e32 v114, v118, v114
	s_waitcnt vmcnt(7)
	v_lshlrev_b32_e32 v140, 16, v192
	v_and_b32_e32 v141, 0xffff0000, v192
	v_lshlrev_b32_e32 v138, 16, v193
	v_and_b32_e32 v139, 0xffff0000, v193
	v_pk_add_f32 v[110:111], v[110:111], v[140:141]
	v_pk_add_f32 v[138:139], v[112:113], v[138:139]
	v_cvt_pk_bf16_f32 v112, v110, v111
	v_cvt_pk_bf16_f32 v113, v138, v139
	global_store_dwordx2 v[136:137], v[112:113], off offset:256
	v_pk_mul_f32 v[112:113], v[110:111], v[110:111]
	v_pk_mul_f32 v[110:111], v[138:139], v[138:139]
	v_add_f32_e32 v112, v112, v113
	v_add_f32_e32 v110, v112, v110
	v_add_f32_e32 v110, v111, v110
	v_add_f32_e32 v110, v114, v110
	s_waitcnt vmcnt(7)
	v_lshlrev_b32_e32 v140, 16, v194
	v_and_b32_e32 v141, 0xffff0000, v194
	v_lshlrev_b32_e32 v138, 16, v195
	v_and_b32_e32 v139, 0xffff0000, v195
	v_pk_add_f32 v[106:107], v[106:107], v[140:141]
	v_pk_add_f32 v[138:139], v[108:109], v[138:139]
	v_cvt_pk_bf16_f32 v108, v106, v107
	v_cvt_pk_bf16_f32 v109, v138, v139
	global_store_dwordx2 v[136:137], v[108:109], off offset:288
	v_pk_mul_f32 v[108:109], v[106:107], v[106:107]
	v_pk_mul_f32 v[106:107], v[138:139], v[138:139]
	v_add_f32_e32 v108, v108, v109
	v_add_f32_e32 v106, v108, v106
	v_add_f32_e32 v106, v107, v106
	v_add_f32_e32 v106, v110, v106
	s_waitcnt vmcnt(7)
	v_lshlrev_b32_e32 v140, 16, v196
	v_and_b32_e32 v141, 0xffff0000, v196
	v_lshlrev_b32_e32 v138, 16, v197
	v_and_b32_e32 v139, 0xffff0000, v197
	v_pk_add_f32 v[102:103], v[102:103], v[140:141]
	v_pk_add_f32 v[138:139], v[104:105], v[138:139]
	v_cvt_pk_bf16_f32 v104, v102, v103
	v_cvt_pk_bf16_f32 v105, v138, v139
	global_store_dwordx2 v[136:137], v[104:105], off offset:320
	v_pk_mul_f32 v[104:105], v[102:103], v[102:103]
	v_pk_mul_f32 v[102:103], v[138:139], v[138:139]
	v_add_f32_e32 v104, v104, v105
	v_add_f32_e32 v102, v104, v102
	v_add_f32_e32 v102, v103, v102
	v_add_f32_e32 v102, v106, v102
	s_waitcnt vmcnt(7)
	v_lshlrev_b32_e32 v140, 16, v198
	v_and_b32_e32 v141, 0xffff0000, v198
	v_pk_add_f32 v[98:99], v[98:99], v[140:141]
	v_lshlrev_b32_e32 v138, 16, v199
	v_and_b32_e32 v139, 0xffff0000, v199
	v_pk_add_f32 v[100:101], v[100:101], v[138:139]
	v_cvt_pk_bf16_f32 v138, v98, v99
	v_pk_mul_f32 v[98:99], v[98:99], v[98:99]
	v_cvt_pk_bf16_f32 v139, v100, v101
	v_pk_mul_f32 v[100:101], v[100:101], v[100:101]
	v_add_f32_e32 v98, v98, v99
	v_add_f32_e32 v98, v98, v100
	v_add_f32_e32 v98, v101, v98
	v_add_f32_e32 v98, v102, v98
	ds_swizzle_b32 v99, v98 offset:swizzle(SWAP,16)
	global_store_dwordx2 v[136:137], v[138:139], off offset:352
	s_waitcnt lgkmcnt(0)
	v_add_f32_e32 v98, v98, v99
	ds_bpermute_b32 v99, v32, v98
	s_and_saveexec_b64 s[0:1], vcc
	s_cbranch_execz .LBB0_1934
	s_waitcnt lgkmcnt(0)
	v_add_f32_e32 v100, v98, v99
	v_lshlrev_b64 v[98:99], 5, v[134:135]
	v_lshl_add_u64 v[98:99], s[12:13], 0, v[98:99]
	v_lshl_add_u64 v[98:99], s[10:11], 2, v[98:99]
	v_lshl_add_u64 v[98:99], v[130:131], 2, v[98:99]
	global_store_dword v[98:99], v100, off
; __device__ __forceinline__ uint2 pack4(float a, float b, float c, float d) { uint2 r; r.x = pk2(a, b); r.y = pk2(c, d); return r; }
;   __device__ __forceinline__ void operator()(EPI_ARGS) {
;     _Pragma("unroll") for (int bj = 0; bj < 2; ++bj) _Pragma("unroll") for (int n = 0; n < 2; ++n) {
;       int t = S_TOK(bj, n); float ss = 0.f;
;       u16* xbp = xb + (long)t * DM;
;       _Pragma("unroll") for (int ai = 0; ai < 2; ++ai) _Pragma("unroll") for (int m = 0; m < 4; ++m) {
;         int f = S_FEAT(ai, m); f32x4 a = acc[ai][bj][m][n];
;         uint2 xv = *(const uint2*)(xbp + f);
;         float v0 = __uint_as_float(xv.x << 16) + a[0], v1 = __uint_as_float(xv.x & 0xffff0000u) + a[1];
;         float v2 = __uint_as_float(xv.y << 16) + a[2], v3 = __uint_as_float(xv.y & 0xffff0000u) + a[3];
;         *(uint2*)(xbp + f) = pack4(v0, v1, v2, v3);
;         ss += v0 * v0 + v1 * v1 + v2 * v2 + v3 * v3;
;       }
;       ss += sx<16>(ss, fq * 16 + fr); ss += sx<32>(ss, fq * 16 + fr);
;       if (fq == 0) part[(long)t * 8 + (fc0 >> 8) * 2 + wr] = ss;
;     }
.LBB0_1934:
	s_or_b64 exec, exec, s[0:1]
	v_add_u32_e32 v98, 16, v134
	s_waitcnt lgkmcnt(0)
	v_ashrrev_i32_e32 v99, 31, v98
	v_lshlrev_b64 v[100:101], 11, v[98:99]
	v_lshl_add_u64 v[100:101], s[6:7], 0, v[100:101]
	v_lshl_add_u64 v[100:101], v[132:133], 1, v[100:101]
	global_load_dwordx2 v[102:103], v[100:101], off
	global_load_dwordx2 v[186:187], v[100:101], off offset:32
	global_load_dwordx2 v[188:189], v[100:101], off offset:64
	global_load_dwordx2 v[190:191], v[100:101], off offset:96
	global_load_dwordx2 v[192:193], v[100:101], off offset:256
	global_load_dwordx2 v[194:195], v[100:101], off offset:288
	global_load_dwordx2 v[196:197], v[100:101], off offset:320
	global_load_dwordx2 v[198:199], v[100:101], off offset:352
	s_waitcnt vmcnt(7)
	v_lshlrev_b32_e32 v104, 16, v102
	v_and_b32_e32 v105, 0xffff0000, v102
	v_lshlrev_b32_e32 v102, 16, v103
	v_and_b32_e32 v103, 0xffff0000, v103
	v_pk_add_f32 v[94:95], v[94:95], v[104:105]
	v_pk_add_f32 v[102:103], v[96:97], v[102:103]
	v_cvt_pk_bf16_f32 v96, v94, v95
	v_cvt_pk_bf16_f32 v97, v102, v103
	global_store_dwordx2 v[100:101], v[96:97], off
	v_pk_mul_f32 v[96:97], v[94:95], v[94:95]
	v_pk_mul_f32 v[94:95], v[102:103], v[102:103]
	s_waitcnt vmcnt(7)
	v_lshlrev_b32_e32 v104, 16, v186
	v_and_b32_e32 v105, 0xffff0000, v186
	v_lshlrev_b32_e32 v102, 16, v187
	v_and_b32_e32 v103, 0xffff0000, v187
	v_pk_add_f32 v[90:91], v[90:91], v[104:105]
	v_pk_add_f32 v[102:103], v[92:93], v[102:103]
	v_cvt_pk_bf16_f32 v92, v90, v91
	v_cvt_pk_bf16_f32 v93, v102, v103
	global_store_dwordx2 v[100:101], v[92:93], off offset:32
	v_pk_mul_f32 v[92:93], v[90:91], v[90:91]
	v_pk_mul_f32 v[90:91], v[102:103], v[102:103]
	v_add_f32_e32 v92, v92, v93
	v_add_f32_e32 v90, v92, v90
	v_add_f32_e32 v90, v91, v90
	v_add_f32_e32 v91, v96, v97
	v_add_f32_e32 v91, v91, v94
	v_add_f32_e32 v91, v95, v91
	v_add_f32_e32 v90, v91, v90
	s_waitcnt vmcnt(7)
	v_lshlrev_b32_e32 v104, 16, v188
	v_and_b32_e32 v105, 0xffff0000, v188
	v_lshlrev_b32_e32 v102, 16, v189
	v_and_b32_e32 v103, 0xffff0000, v189
	v_pk_add_f32 v[86:87], v[86:87], v[104:105]
	v_pk_add_f32 v[102:103], v[88:89], v[102:103]
	v_cvt_pk_bf16_f32 v88, v86, v87
	v_cvt_pk_bf16_f32 v89, v102, v103
	global_store_dwordx2 v[100:101], v[88:89], off offset:64
	v_pk_mul_f32 v[88:89], v[86:87], v[86:87]
	v_pk_mul_f32 v[86:87], v[102:103], v[102:103]
	v_add_f32_e32 v88, v88, v89
	v_add_f32_e32 v86, v88, v86
	v_add_f32_e32 v86, v87, v86
	v_add_f32_e32 v86, v90, v86
	s_waitcnt vmcnt(7)
	v_lshlrev_b32_e32 v104, 16, v190
	v_and_b32_e32 v105, 0xffff0000, v190
	v_lshlrev_b32_e32 v102, 16, v191
	v_and_b32_e32 v103, 0xffff0000, v191
	v_pk_add_f32 v[82:83], v[82:83], v[104:105]
	v_pk_add_f32 v[102:103], v[84:85], v[102:103]
	v_cvt_pk_bf16_f32 v84, v82, v83
	v_cvt_pk_bf16_f32 v85, v102, v103
	global_store_dwordx2 v[100:101], v[84:85], off offset:96
	v_pk_mul_f32 v[84:85], v[82:83], v[82:83]
	v_pk_mul_f32 v[82:83], v[102:103], v[102:103]
	v_add_f32_e32 v84, v84, v85
	v_add_f32_e32 v82, v84, v82
	v_add_f32_e32 v82, v83, v82
	v_add_f32_e32 v82, v86, v82
	s_waitcnt vmcnt(7)
	v_lshlrev_b32_e32 v104, 16, v192
	v_and_b32_e32 v105, 0xffff0000, v192
	v_lshlrev_b32_e32 v102, 16, v193
	v_and_b32_e32 v103, 0xffff0000, v193
	v_pk_add_f32 v[78:79], v[78:79], v[104:105]
	v_pk_add_f32 v[102:103], v[80:81], v[102:103]
	v_cvt_pk_bf16_f32 v80, v78, v79
	v_cvt_pk_bf16_f32 v81, v102, v103
	global_store_dwordx2 v[100:101], v[80:81], off offset:256
	v_pk_mul_f32 v[80:81], v[78:79], v[78:79]
	v_pk_mul_f32 v[78:79], v[102:103], v[102:103]
	v_add_f32_e32 v80, v80, v81
	v_add_f32_e32 v78, v80, v78
	v_add_f32_e32 v78, v79, v78
	v_add_f32_e32 v78, v82, v78
	s_waitcnt vmcnt(7)
	v_lshlrev_b32_e32 v104, 16, v194
	v_and_b32_e32 v105, 0xffff0000, v194
	v_lshlrev_b32_e32 v102, 16, v195
	v_and_b32_e32 v103, 0xffff0000, v195
	v_pk_add_f32 v[74:75], v[74:75], v[104:105]
	v_pk_add_f32 v[102:103], v[76:77], v[102:103]
	v_cvt_pk_bf16_f32 v76, v74, v75
	v_cvt_pk_bf16_f32 v77, v102, v103
	global_store_dwordx2 v[100:101], v[76:77], off offset:288
	v_pk_mul_f32 v[76:77], v[74:75], v[74:75]
	v_pk_mul_f32 v[74:75], v[102:103], v[102:103]
	v_add_f32_e32 v76, v76, v77
	v_add_f32_e32 v74, v76, v74
	v_add_f32_e32 v74, v75, v74
	v_add_f32_e32 v74, v78, v74
	s_waitcnt vmcnt(7)
	v_lshlrev_b32_e32 v104, 16, v196
	v_and_b32_e32 v105, 0xffff0000, v196
	v_lshlrev_b32_e32 v102, 16, v197
	v_and_b32_e32 v103, 0xffff0000, v197
	v_pk_add_f32 v[70:71], v[70:71], v[104:105]
	v_pk_add_f32 v[102:103], v[72:73], v[102:103]
	v_cvt_pk_bf16_f32 v72, v70, v71
	v_cvt_pk_bf16_f32 v73, v102, v103
	global_store_dwordx2 v[100:101], v[72:73], off offset:320
	v_pk_mul_f32 v[72:73], v[70:71], v[70:71]
	v_pk_mul_f32 v[70:71], v[102:103], v[102:103]
	v_add_f32_e32 v72, v72, v73
	v_add_f32_e32 v70, v72, v70
	v_add_f32_e32 v70, v71, v70
	v_add_f32_e32 v70, v74, v70
	s_waitcnt vmcnt(7)
	v_lshlrev_b32_e32 v104, 16, v198
	v_and_b32_e32 v105, 0xffff0000, v198
	v_pk_add_f32 v[66:67], v[66:67], v[104:105]
	v_lshlrev_b32_e32 v102, 16, v199
	v_and_b32_e32 v103, 0xffff0000, v199
	v_pk_add_f32 v[68:69], v[68:69], v[102:103]
	v_cvt_pk_bf16_f32 v102, v66, v67
	v_pk_mul_f32 v[66:67], v[66:67], v[66:67]
	v_cvt_pk_bf16_f32 v103, v68, v69
	v_pk_mul_f32 v[68:69], v[68:69], v[68:69]
	v_add_f32_e32 v66, v66, v67
	v_add_f32_e32 v66, v66, v68
	v_add_f32_e32 v66, v69, v66
	v_add_f32_e32 v66, v70, v66
	ds_swizzle_b32 v67, v66 offset:swizzle(SWAP,16)
	global_store_dwordx2 v[100:101], v[102:103], off offset:352
	s_waitcnt lgkmcnt(0)
	v_add_f32_e32 v66, v66, v67
	ds_bpermute_b32 v67, v32, v66
	s_and_saveexec_b64 s[0:1], vcc
	s_cbranch_execz .LBB0_1936
	s_waitcnt lgkmcnt(0)
	v_add_f32_e32 v68, v66, v67
	v_lshlrev_b64 v[66:67], 5, v[98:99]
	v_lshl_add_u64 v[66:67], s[12:13], 0, v[66:67]
	v_lshl_add_u64 v[66:67], s[10:11], 2, v[66:67]
	v_lshl_add_u64 v[66:67], v[130:131], 2, v[66:67]
	global_store_dword v[66:67], v68, off
; __device__ __forceinline__ uint2 pack4(float a, float b, float c, float d) { uint2 r; r.x = pk2(a, b); r.y = pk2(c, d); return r; }
;   __device__ __forceinline__ void operator()(EPI_ARGS) {
;     _Pragma("unroll") for (int bj = 0; bj < 2; ++bj) _Pragma("unroll") for (int n = 0; n < 2; ++n) {
;       int t = S_TOK(bj, n); float ss = 0.f;
;       u16* xbp = xb + (long)t * DM;
;       _Pragma("unroll") for (int ai = 0; ai < 2; ++ai) _Pragma("unroll") for (int m = 0; m < 4; ++m) {
;         int f = S_FEAT(ai, m); f32x4 a = acc[ai][bj][m][n];
;         uint2 xv = *(const uint2*)(xbp + f);
;         float v0 = __uint_as_float(xv.x << 16) + a[0], v1 = __uint_as_float(xv.x & 0xffff0000u) + a[1];
;         float v2 = __uint_as_float(xv.y << 16) + a[2], v3 = __uint_as_float(xv.y & 0xffff0000u) + a[3];
;         *(uint2*)(xbp + f) = pack4(v0, v1, v2, v3);
;         ss += v0 * v0 + v1 * v1 + v2 * v2 + v3 * v3;
;       }
;       ss += sx<16>(ss, fq * 16 + fr); ss += sx<32>(ss, fq * 16 + fr);
;       if (fq == 0) part[(long)t * 8 + (fc0 >> 8) * 2 + wr] = ss;
;     }
.LBB0_1936:
	s_or_b64 exec, exec, s[0:1]
	v_add_u32_e32 v66, 0x80, v134
	s_waitcnt lgkmcnt(0)
	v_ashrrev_i32_e32 v67, 31, v66
	v_lshlrev_b64 v[68:69], 11, v[66:67]
	v_lshl_add_u64 v[68:69], s[6:7], 0, v[68:69]
	v_lshl_add_u64 v[68:69], v[132:133], 1, v[68:69]
	global_load_dwordx2 v[70:71], v[68:69], off
	global_load_dwordx2 v[186:187], v[68:69], off offset:32
	global_load_dwordx2 v[188:189], v[68:69], off offset:64
	global_load_dwordx2 v[190:191], v[68:69], off offset:96
	global_load_dwordx2 v[192:193], v[68:69], off offset:256
	global_load_dwordx2 v[194:195], v[68:69], off offset:288
	global_load_dwordx2 v[196:197], v[68:69], off offset:320
	global_load_dwordx2 v[198:199], v[68:69], off offset:352
	s_waitcnt vmcnt(7)
	v_lshlrev_b32_e32 v72, 16, v70
	v_and_b32_e32 v73, 0xffff0000, v70
	v_lshlrev_b32_e32 v70, 16, v71
	v_and_b32_e32 v71, 0xffff0000, v71
	v_pk_add_f32 v[62:63], v[62:63], v[72:73]
	v_pk_add_f32 v[70:71], v[64:65], v[70:71]
	v_cvt_pk_bf16_f32 v64, v62, v63
	v_cvt_pk_bf16_f32 v65, v70, v71
	global_store_dwordx2 v[68:69], v[64:65], off
	v_pk_mul_f32 v[64:65], v[62:63], v[62:63]
	v_pk_mul_f32 v[62:63], v[70:71], v[70:71]
	s_waitcnt vmcnt(7)
	v_lshlrev_b32_e32 v72, 16, v186
	v_and_b32_e32 v73, 0xffff0000, v186
	v_lshlrev_b32_e32 v70, 16, v187
	v_and_b32_e32 v71, 0xffff0000, v187
	v_pk_add_f32 v[58:59], v[58:59], v[72:73]
	v_pk_add_f32 v[70:71], v[60:61], v[70:71]
	v_cvt_pk_bf16_f32 v60, v58, v59
	v_cvt_pk_bf16_f32 v61, v70, v71
	global_store_dwordx2 v[68:69], v[60:61], off offset:32
	v_pk_mul_f32 v[60:61], v[58:59], v[58:59]
	v_pk_mul_f32 v[58:59], v[70:71], v[70:71]
	v_add_f32_e32 v60, v60, v61
	v_add_f32_e32 v58, v60, v58
	v_add_f32_e32 v58, v59, v58
	v_add_f32_e32 v59, v64, v65
	v_add_f32_e32 v59, v59, v62
	v_add_f32_e32 v59, v63, v59
	v_add_f32_e32 v58, v59, v58
	s_waitcnt vmcnt(7)
	v_lshlrev_b32_e32 v72, 16, v188
	v_and_b32_e32 v73, 0xffff0000, v188
	v_lshlrev_b32_e32 v70, 16, v189
	v_and_b32_e32 v71, 0xffff0000, v189
	v_pk_add_f32 v[54:55], v[54:55], v[72:73]
	v_pk_add_f32 v[70:71], v[56:57], v[70:71]
	v_cvt_pk_bf16_f32 v56, v54, v55
	v_cvt_pk_bf16_f32 v57, v70, v71
	global_store_dwordx2 v[68:69], v[56:57], off offset:64
	v_pk_mul_f32 v[56:57], v[54:55], v[54:55]
	v_pk_mul_f32 v[54:55], v[70:71], v[70:71]
	v_add_f32_e32 v56, v56, v57
	v_add_f32_e32 v54, v56, v54
	v_add_f32_e32 v54, v55, v54
	v_add_f32_e32 v54, v58, v54
	s_waitcnt vmcnt(7)
	v_lshlrev_b32_e32 v72, 16, v190
	v_and_b32_e32 v73, 0xffff0000, v190
	v_lshlrev_b32_e32 v70, 16, v191
	v_and_b32_e32 v71, 0xffff0000, v191
	v_pk_add_f32 v[50:51], v[50:51], v[72:73]
	v_pk_add_f32 v[70:71], v[52:53], v[70:71]
	v_cvt_pk_bf16_f32 v52, v50, v51
	v_cvt_pk_bf16_f32 v53, v70, v71
	global_store_dwordx2 v[68:69], v[52:53], off offset:96
	v_pk_mul_f32 v[52:53], v[50:51], v[50:51]
	v_pk_mul_f32 v[50:51], v[70:71], v[70:71]
	v_add_f32_e32 v52, v52, v53
	v_add_f32_e32 v50, v52, v50
	v_add_f32_e32 v50, v51, v50
	v_add_f32_e32 v50, v54, v50
	s_waitcnt vmcnt(7)
	v_lshlrev_b32_e32 v72, 16, v192
	v_and_b32_e32 v73, 0xffff0000, v192
	v_lshlrev_b32_e32 v70, 16, v193
	v_and_b32_e32 v71, 0xffff0000, v193
	v_pk_add_f32 v[46:47], v[46:47], v[72:73]
	v_pk_add_f32 v[70:71], v[48:49], v[70:71]
	v_cvt_pk_bf16_f32 v48, v46, v47
	v_cvt_pk_bf16_f32 v49, v70, v71
	global_store_dwordx2 v[68:69], v[48:49], off offset:256
	v_pk_mul_f32 v[48:49], v[46:47], v[46:47]
	v_pk_mul_f32 v[46:47], v[70:71], v[70:71]
	v_add_f32_e32 v48, v48, v49
	v_add_f32_e32 v46, v48, v46
	v_add_f32_e32 v46, v47, v46
	v_add_f32_e32 v46, v50, v46
	s_waitcnt vmcnt(7)
	v_lshlrev_b32_e32 v72, 16, v194
	v_and_b32_e32 v73, 0xffff0000, v194
	v_lshlrev_b32_e32 v70, 16, v195
	v_and_b32_e32 v71, 0xffff0000, v195
	v_pk_add_f32 v[42:43], v[42:43], v[72:73]
	v_pk_add_f32 v[70:71], v[44:45], v[70:71]
	v_cvt_pk_bf16_f32 v44, v42, v43
	v_cvt_pk_bf16_f32 v45, v70, v71
	global_store_dwordx2 v[68:69], v[44:45], off offset:288
	v_pk_mul_f32 v[44:45], v[42:43], v[42:43]
	v_pk_mul_f32 v[42:43], v[70:71], v[70:71]
	v_add_f32_e32 v44, v44, v45
	v_add_f32_e32 v42, v44, v42
	v_add_f32_e32 v42, v43, v42
	v_add_f32_e32 v42, v46, v42
	s_waitcnt vmcnt(7)
	v_lshlrev_b32_e32 v72, 16, v196
	v_and_b32_e32 v73, 0xffff0000, v196
	v_lshlrev_b32_e32 v70, 16, v197
	v_and_b32_e32 v71, 0xffff0000, v197
	v_pk_add_f32 v[38:39], v[38:39], v[72:73]
	v_pk_add_f32 v[70:71], v[40:41], v[70:71]
	v_cvt_pk_bf16_f32 v40, v38, v39
	v_cvt_pk_bf16_f32 v41, v70, v71
	global_store_dwordx2 v[68:69], v[40:41], off offset:320
	v_pk_mul_f32 v[40:41], v[38:39], v[38:39]
	v_pk_mul_f32 v[38:39], v[70:71], v[70:71]
	v_add_f32_e32 v40, v40, v41
	v_add_f32_e32 v38, v40, v38
	v_add_f32_e32 v38, v39, v38
	v_add_f32_e32 v38, v42, v38
	s_waitcnt vmcnt(7)
	v_lshlrev_b32_e32 v72, 16, v198
	v_and_b32_e32 v73, 0xffff0000, v198
	v_pk_add_f32 v[34:35], v[34:35], v[72:73]
	v_lshlrev_b32_e32 v70, 16, v199
	v_and_b32_e32 v71, 0xffff0000, v199
	v_pk_add_f32 v[36:37], v[36:37], v[70:71]
	v_cvt_pk_bf16_f32 v70, v34, v35
	v_pk_mul_f32 v[34:35], v[34:35], v[34:35]
	v_cvt_pk_bf16_f32 v71, v36, v37
	v_pk_mul_f32 v[36:37], v[36:37], v[36:37]
	v_add_f32_e32 v34, v34, v35
	v_add_f32_e32 v34, v34, v36
	v_add_f32_e32 v34, v37, v34
	v_add_f32_e32 v34, v38, v34
	ds_swizzle_b32 v35, v34 offset:swizzle(SWAP,16)
	global_store_dwordx2 v[68:69], v[70:71], off offset:352
	s_waitcnt lgkmcnt(0)
	v_add_f32_e32 v34, v34, v35
	ds_bpermute_b32 v35, v32, v34
	s_and_saveexec_b64 s[0:1], vcc
	s_cbranch_execz .LBB0_1938
	s_waitcnt lgkmcnt(0)
	v_add_f32_e32 v36, v34, v35
	v_lshlrev_b64 v[34:35], 5, v[66:67]
	v_lshl_add_u64 v[34:35], s[12:13], 0, v[34:35]
	v_lshl_add_u64 v[34:35], s[10:11], 2, v[34:35]
	v_lshl_add_u64 v[34:35], v[130:131], 2, v[34:35]
	global_store_dword v[34:35], v36, off
; __device__ __forceinline__ uint2 pack4(float a, float b, float c, float d) { uint2 r; r.x = pk2(a, b); r.y = pk2(c, d); return r; }
;   __device__ __forceinline__ void operator()(EPI_ARGS) {
;     _Pragma("unroll") for (int bj = 0; bj < 2; ++bj) _Pragma("unroll") for (int n = 0; n < 2; ++n) {
;       int t = S_TOK(bj, n); float ss = 0.f;
;       u16* xbp = xb + (long)t * DM;
;       _Pragma("unroll") for (int ai = 0; ai < 2; ++ai) _Pragma("unroll") for (int m = 0; m < 4; ++m) {
;         int f = S_FEAT(ai, m); f32x4 a = acc[ai][bj][m][n];
;         uint2 xv = *(const uint2*)(xbp + f);
;         float v0 = __uint_as_float(xv.x << 16) + a[0], v1 = __uint_as_float(xv.x & 0xffff0000u) + a[1];
;         float v2 = __uint_as_float(xv.y << 16) + a[2], v3 = __uint_as_float(xv.y & 0xffff0000u) + a[3];
;         *(uint2*)(xbp + f) = pack4(v0, v1, v2, v3);
;         ss += v0 * v0 + v1 * v1 + v2 * v2 + v3 * v3;
;       }
;       ss += sx<16>(ss, fq * 16 + fr); ss += sx<32>(ss, fq * 16 + fr);
;       if (fq == 0) part[(long)t * 8 + (fc0 >> 8) * 2 + wr] = ss;
;     }
.LBB0_1938:
	s_or_b64 exec, exec, s[0:1]
	v_add_u32_e32 v34, 0x90, v134
	s_waitcnt lgkmcnt(0)
	v_ashrrev_i32_e32 v35, 31, v34
	v_lshlrev_b64 v[36:37], 11, v[34:35]
	v_lshl_add_u64 v[36:37], s[6:7], 0, v[36:37]
	v_lshl_add_u64 v[36:37], v[132:133], 1, v[36:37]
	global_load_dwordx2 v[38:39], v[36:37], off
	global_load_dwordx2 v[186:187], v[36:37], off offset:32
	global_load_dwordx2 v[188:189], v[36:37], off offset:64
	global_load_dwordx2 v[190:191], v[36:37], off offset:96
	global_load_dwordx2 v[192:193], v[36:37], off offset:256
	global_load_dwordx2 v[194:195], v[36:37], off offset:288
	global_load_dwordx2 v[196:197], v[36:37], off offset:320
	global_load_dwordx2 v[198:199], v[36:37], off offset:352
	s_waitcnt vmcnt(7)
	v_lshlrev_b32_e32 v40, 16, v38
	v_and_b32_e32 v41, 0xffff0000, v38
	v_lshlrev_b32_e32 v38, 16, v39
	v_and_b32_e32 v39, 0xffff0000, v39
	v_pk_add_f32 v[28:29], v[28:29], v[40:41]
	v_pk_add_f32 v[38:39], v[30:31], v[38:39]
	v_cvt_pk_bf16_f32 v30, v28, v29
	v_cvt_pk_bf16_f32 v31, v38, v39
	global_store_dwordx2 v[36:37], v[30:31], off
	v_pk_mul_f32 v[30:31], v[28:29], v[28:29]
	v_pk_mul_f32 v[28:29], v[38:39], v[38:39]
	s_waitcnt vmcnt(7)
	v_lshlrev_b32_e32 v40, 16, v186
	v_and_b32_e32 v41, 0xffff0000, v186
	v_lshlrev_b32_e32 v38, 16, v187
	v_and_b32_e32 v39, 0xffff0000, v187
	v_pk_add_f32 v[24:25], v[24:25], v[40:41]
	v_pk_add_f32 v[38:39], v[26:27], v[38:39]
	v_cvt_pk_bf16_f32 v26, v24, v25
	v_cvt_pk_bf16_f32 v27, v38, v39
	global_store_dwordx2 v[36:37], v[26:27], off offset:32
	v_pk_mul_f32 v[26:27], v[24:25], v[24:25]
	v_pk_mul_f32 v[24:25], v[38:39], v[38:39]
	v_add_f32_e32 v26, v26, v27
	v_add_f32_e32 v24, v26, v24
	v_add_f32_e32 v24, v25, v24
	v_add_f32_e32 v25, v30, v31
	v_add_f32_e32 v25, v25, v28
	v_add_f32_e32 v25, v29, v25
	v_add_f32_e32 v24, v25, v24
	s_waitcnt vmcnt(7)
	v_lshlrev_b32_e32 v40, 16, v188
	v_and_b32_e32 v41, 0xffff0000, v188
	v_lshlrev_b32_e32 v38, 16, v189
	v_and_b32_e32 v39, 0xffff0000, v189
	v_pk_add_f32 v[20:21], v[20:21], v[40:41]
	v_pk_add_f32 v[38:39], v[22:23], v[38:39]
	v_cvt_pk_bf16_f32 v22, v20, v21
	v_cvt_pk_bf16_f32 v23, v38, v39
	global_store_dwordx2 v[36:37], v[22:23], off offset:64
	v_pk_mul_f32 v[22:23], v[20:21], v[20:21]
	v_pk_mul_f32 v[20:21], v[38:39], v[38:39]
	v_add_f32_e32 v22, v22, v23
	v_add_f32_e32 v20, v22, v20
	v_add_f32_e32 v20, v21, v20
	v_add_f32_e32 v20, v24, v20
	s_waitcnt vmcnt(7)
	v_lshlrev_b32_e32 v40, 16, v190
	v_and_b32_e32 v41, 0xffff0000, v190
	v_lshlrev_b32_e32 v38, 16, v191
	v_and_b32_e32 v39, 0xffff0000, v191
	v_pk_add_f32 v[16:17], v[16:17], v[40:41]
	v_pk_add_f32 v[38:39], v[18:19], v[38:39]
	v_cvt_pk_bf16_f32 v18, v16, v17
	v_cvt_pk_bf16_f32 v19, v38, v39
	global_store_dwordx2 v[36:37], v[18:19], off offset:96
	v_pk_mul_f32 v[18:19], v[16:17], v[16:17]
	v_pk_mul_f32 v[16:17], v[38:39], v[38:39]
	v_add_f32_e32 v18, v18, v19
	v_add_f32_e32 v16, v18, v16
	v_add_f32_e32 v16, v17, v16
	v_add_f32_e32 v16, v20, v16
	s_waitcnt vmcnt(7)
	v_lshlrev_b32_e32 v40, 16, v192
	v_and_b32_e32 v41, 0xffff0000, v192
	v_lshlrev_b32_e32 v38, 16, v193
	v_and_b32_e32 v39, 0xffff0000, v193
	v_pk_add_f32 v[12:13], v[12:13], v[40:41]
	v_pk_add_f32 v[38:39], v[14:15], v[38:39]
	v_cvt_pk_bf16_f32 v14, v12, v13
	v_cvt_pk_bf16_f32 v15, v38, v39
	global_store_dwordx2 v[36:37], v[14:15], off offset:256
	v_pk_mul_f32 v[14:15], v[12:13], v[12:13]
	v_pk_mul_f32 v[12:13], v[38:39], v[38:39]
	v_add_f32_e32 v14, v14, v15
	v_add_f32_e32 v12, v14, v12
	v_add_f32_e32 v12, v13, v12
	v_add_f32_e32 v12, v16, v12
	s_waitcnt vmcnt(7)
	v_lshlrev_b32_e32 v40, 16, v194
	v_and_b32_e32 v41, 0xffff0000, v194
	v_lshlrev_b32_e32 v38, 16, v195
	v_and_b32_e32 v39, 0xffff0000, v195
	v_pk_add_f32 v[8:9], v[8:9], v[40:41]
	v_pk_add_f32 v[38:39], v[10:11], v[38:39]
	v_cvt_pk_bf16_f32 v10, v8, v9
	v_cvt_pk_bf16_f32 v11, v38, v39
	global_store_dwordx2 v[36:37], v[10:11], off offset:288
	v_pk_mul_f32 v[10:11], v[8:9], v[8:9]
	v_pk_mul_f32 v[8:9], v[38:39], v[38:39]
	v_add_f32_e32 v10, v10, v11
	v_add_f32_e32 v8, v10, v8
	v_add_f32_e32 v8, v9, v8
	v_add_f32_e32 v8, v12, v8
	s_waitcnt vmcnt(7)
	v_lshlrev_b32_e32 v40, 16, v196
	v_and_b32_e32 v41, 0xffff0000, v196
	v_lshlrev_b32_e32 v38, 16, v197
	v_and_b32_e32 v39, 0xffff0000, v197
	v_pk_add_f32 v[4:5], v[4:5], v[40:41]
	v_pk_add_f32 v[38:39], v[6:7], v[38:39]
	v_cvt_pk_bf16_f32 v6, v4, v5
	v_cvt_pk_bf16_f32 v7, v38, v39
	global_store_dwordx2 v[36:37], v[6:7], off offset:320
	v_pk_mul_f32 v[6:7], v[4:5], v[4:5]
	v_pk_mul_f32 v[4:5], v[38:39], v[38:39]
	v_add_f32_e32 v6, v6, v7
	v_add_f32_e32 v4, v6, v4
	v_add_f32_e32 v4, v5, v4
	v_add_f32_e32 v4, v8, v4
	s_waitcnt vmcnt(7)
	v_lshlrev_b32_e32 v40, 16, v198
	v_and_b32_e32 v41, 0xffff0000, v198
	v_pk_add_f32 v[0:1], v[0:1], v[40:41]
	v_lshlrev_b32_e32 v38, 16, v199
	v_and_b32_e32 v39, 0xffff0000, v199
	v_pk_add_f32 v[2:3], v[2:3], v[38:39]
	v_cvt_pk_bf16_f32 v38, v0, v1
	v_pk_mul_f32 v[0:1], v[0:1], v[0:1]
	v_cvt_pk_bf16_f32 v39, v2, v3
	v_pk_mul_f32 v[2:3], v[2:3], v[2:3]
	v_add_f32_e32 v0, v0, v1
	v_add_f32_e32 v0, v0, v2
	v_add_f32_e32 v0, v3, v0
	v_add_f32_e32 v0, v4, v0
	ds_swizzle_b32 v1, v0 offset:swizzle(SWAP,16)
	global_store_dwordx2 v[36:37], v[38:39], off offset:352
	s_waitcnt lgkmcnt(0)
	v_add_f32_e32 v0, v0, v1
	ds_bpermute_b32 v1, v32, v0
	s_and_saveexec_b64 s[0:1], vcc
	s_cbranch_execz .LBB0_1911
	s_waitcnt lgkmcnt(0)
	v_add_f32_e32 v2, v0, v1
	v_lshlrev_b64 v[0:1], 5, v[34:35]
	v_lshl_add_u64 v[0:1], s[12:13], 0, v[0:1]
	v_lshl_add_u64 v[0:1], s[10:11], 2, v[0:1]
	v_lshl_add_u64 v[0:1], v[130:131], 2, v[0:1]
	global_store_dword v[0:1], v2, off
	s_branch .LBB0_1911

; __device__ __forceinline__ uint2 pack4(float a, float b, float c, float d) { uint2 r; r.x = pk2(a, b); r.y = pk2(c, d); return r; }
;   __device__ __forceinline__ void operator()(EPI_ARGS) {
;     _Pragma("unroll") for (int bj = 0; bj < 2; ++bj) _Pragma("unroll") for (int n = 0; n < 2; ++n) {
;       int t = S_TOK(bj, n); float ss = 0.f;
;       u16* xbp = xb + (long)t * DM;
;       _Pragma("unroll") for (int ai = 0; ai < 2; ++ai) _Pragma("unroll") for (int m = 0; m < 4; ++m) {
;         int f = S_FEAT(ai, m); f32x4 a = acc[ai][bj][m][n];
;         uint2 xv = *(const uint2*)(xbp + f);
;         float v0 = __uint_as_float(xv.x << 16) + a[0], v1 = __uint_as_float(xv.x & 0xffff0000u) + a[1];
;         float v2 = __uint_as_float(xv.y << 16) + a[2], v3 = __uint_as_float(xv.y & 0xffff0000u) + a[3];
;         *(uint2*)(xbp + f) = pack4(v0, v1, v2, v3);
;         ss += v0 * v0 + v1 * v1 + v2 * v2 + v3 * v3;
;       }
;       ss += sx<16>(ss, fq * 16 + fr); ss += sx<32>(ss, fq * 16 + fr);
;       if (fq == 0) part[(long)t * 8 + (fc0 >> 8) * 2 + wr] = ss;
;     }
.LBB0_2341:
	s_mov_b32 s0, -1
	s_ashr_i32 s6, s17, 7
	v_mbcnt_lo_u32_b32 v32, s0, 0
	v_mbcnt_hi_u32_b32 v32, s0, v32
	v_or_b32_e32 v32, s97, v32
	s_ashr_i32 s7, s6, 31
	v_ashrrev_i32_e32 v130, 8, v32
	v_and_b32_e32 v131, 15, v32
	v_bfe_u32 v133, v32, 4, 2
	v_lshrrev_b32_e32 v32, 1, v32
	v_and_b32_e32 v32, 0x60, v32
	v_add3_u32 v134, v131, s18, v32
	v_lshl_add_u32 v32, v130, 6, s17
	v_ashrrev_i32_e32 v135, 31, v134
	v_lshl_or_b32 v132, v133, 2, v32
	v_lshlrev_b64 v[136:137], 11, v[134:135]
	v_lshlrev_b32_e32 v32, 6, v133
	v_cmp_eq_u32_e32 vcc, 0, v133
	v_lshl_add_u64 v[136:137], s[8:9], 0, v[136:137]
	v_ashrrev_i32_e32 v133, 31, v132
	v_lshl_add_u64 v[136:137], v[132:133], 1, v[136:137]
	global_load_dwordx2 v[138:139], v[136:137], off
	global_load_dwordx2 v[186:187], v[136:137], off offset:32
	global_load_dwordx2 v[188:189], v[136:137], off offset:64
	global_load_dwordx2 v[190:191], v[136:137], off offset:96
	global_load_dwordx2 v[192:193], v[136:137], off offset:256
	global_load_dwordx2 v[194:195], v[136:137], off offset:288
	global_load_dwordx2 v[196:197], v[136:137], off offset:320
	global_load_dwordx2 v[198:199], v[136:137], off offset:352
	v_lshlrev_b32_e32 v131, 2, v131
	v_bitop3_b32 v32, v32, s57, v131 bitop3:0x36
	v_ashrrev_i32_e32 v131, 31, v130
	s_waitcnt vmcnt(7)
	v_lshlrev_b32_e32 v140, 16, v138
	v_and_b32_e32 v141, 0xffff0000, v138
	v_lshlrev_b32_e32 v138, 16, v139
	v_and_b32_e32 v139, 0xffff0000, v139
	v_pk_add_f32 v[126:127], v[126:127], v[140:141]
	v_pk_add_f32 v[138:139], v[128:129], v[138:139]
	v_cvt_pk_bf16_f32 v128, v126, v127
	v_cvt_pk_bf16_f32 v129, v138, v139
	global_store_dwordx2 v[136:137], v[128:129], off
	v_pk_mul_f32 v[128:129], v[126:127], v[126:127]
	v_pk_mul_f32 v[126:127], v[138:139], v[138:139]
	s_waitcnt vmcnt(7)
	v_lshlrev_b32_e32 v140, 16, v186
	v_and_b32_e32 v141, 0xffff0000, v186
	v_lshlrev_b32_e32 v138, 16, v187
	v_and_b32_e32 v139, 0xffff0000, v187
	v_pk_add_f32 v[122:123], v[122:123], v[140:141]
	v_pk_add_f32 v[138:139], v[124:125], v[138:139]
	v_cvt_pk_bf16_f32 v124, v122, v123
	v_cvt_pk_bf16_f32 v125, v138, v139
	global_store_dwordx2 v[136:137], v[124:125], off offset:32
	v_pk_mul_f32 v[124:125], v[122:123], v[122:123]
	v_pk_mul_f32 v[122:123], v[138:139], v[138:139]
	v_add_f32_e32 v124, v124, v125
	v_add_f32_e32 v122, v124, v122
	v_add_f32_e32 v122, v123, v122
	v_add_f32_e32 v123, v128, v129
	v_add_f32_e32 v123, v123, v126
	v_add_f32_e32 v123, v127, v123
	v_add_f32_e32 v122, v123, v122
	s_waitcnt vmcnt(7)
	v_lshlrev_b32_e32 v140, 16, v188
	v_and_b32_e32 v141, 0xffff0000, v188
	v_lshlrev_b32_e32 v138, 16, v189
	v_and_b32_e32 v139, 0xffff0000, v189
	v_pk_add_f32 v[118:119], v[118:119], v[140:141]
	v_pk_add_f32 v[138:139], v[120:121], v[138:139]
	v_cvt_pk_bf16_f32 v120, v118, v119
	v_cvt_pk_bf16_f32 v121, v138, v139
	global_store_dwordx2 v[136:137], v[120:121], off offset:64
	v_pk_mul_f32 v[120:121], v[118:119], v[118:119]
	v_pk_mul_f32 v[118:119], v[138:139], v[138:139]
	v_add_f32_e32 v120, v120, v121
	v_add_f32_e32 v118, v120, v118
	v_add_f32_e32 v118, v119, v118
	v_add_f32_e32 v118, v122, v118
	s_waitcnt vmcnt(7)
	v_lshlrev_b32_e32 v140, 16, v190
	v_and_b32_e32 v141, 0xffff0000, v190
	v_lshlrev_b32_e32 v138, 16, v191
	v_and_b32_e32 v139, 0xffff0000, v191
	v_pk_add_f32 v[114:115], v[114:115], v[140:141]
	v_pk_add_f32 v[138:139], v[116:117], v[138:139]
	v_cvt_pk_bf16_f32 v116, v114, v115
	v_cvt_pk_bf16_f32 v117, v138, v139
	global_store_dwordx2 v[136:137], v[116:117], off offset:96
	v_pk_mul_f32 v[116:117], v[114:115], v[114:115]
	v_pk_mul_f32 v[114:115], v[138:139], v[138:139]
	v_add_f32_e32 v116, v116, v117
	v_add_f32_e32 v114, v116, v114
	v_add_f32_e32 v114, v115, v114
	v_add_f32_e32 v114, v118, v114
	s_waitcnt vmcnt(7)
	v_lshlrev_b32_e32 v140, 16, v192
	v_and_b32_e32 v141, 0xffff0000, v192
	v_lshlrev_b32_e32 v138, 16, v193
	v_and_b32_e32 v139, 0xffff0000, v193
	v_pk_add_f32 v[110:111], v[110:111], v[140:141]
	v_pk_add_f32 v[138:139], v[112:113], v[138:139]
	v_cvt_pk_bf16_f32 v112, v110, v111
	v_cvt_pk_bf16_f32 v113, v138, v139
	global_store_dwordx2 v[136:137], v[112:113], off offset:256
	v_pk_mul_f32 v[112:113], v[110:111], v[110:111]
	v_pk_mul_f32 v[110:111], v[138:139], v[138:139]
	v_add_f32_e32 v112, v112, v113
	v_add_f32_e32 v110, v112, v110
	v_add_f32_e32 v110, v111, v110
	v_add_f32_e32 v110, v114, v110
	s_waitcnt vmcnt(7)
	v_lshlrev_b32_e32 v140, 16, v194
	v_and_b32_e32 v141, 0xffff0000, v194
	v_lshlrev_b32_e32 v138, 16, v195
	v_and_b32_e32 v139, 0xffff0000, v195
	v_pk_add_f32 v[106:107], v[106:107], v[140:141]
	v_pk_add_f32 v[138:139], v[108:109], v[138:139]
	v_cvt_pk_bf16_f32 v108, v106, v107
	v_cvt_pk_bf16_f32 v109, v138, v139
	global_store_dwordx2 v[136:137], v[108:109], off offset:288
	v_pk_mul_f32 v[108:109], v[106:107], v[106:107]
	v_pk_mul_f32 v[106:107], v[138:139], v[138:139]
	v_add_f32_e32 v108, v108, v109
	v_add_f32_e32 v106, v108, v106
	v_add_f32_e32 v106, v107, v106
	v_add_f32_e32 v106, v110, v106
	s_waitcnt vmcnt(7)
	v_lshlrev_b32_e32 v140, 16, v196
	v_and_b32_e32 v141, 0xffff0000, v196
	v_lshlrev_b32_e32 v138, 16, v197
	v_and_b32_e32 v139, 0xffff0000, v197
	v_pk_add_f32 v[102:103], v[102:103], v[140:141]
	v_pk_add_f32 v[138:139], v[104:105], v[138:139]
	v_cvt_pk_bf16_f32 v104, v102, v103
	v_cvt_pk_bf16_f32 v105, v138, v139
	global_store_dwordx2 v[136:137], v[104:105], off offset:320
	v_pk_mul_f32 v[104:105], v[102:103], v[102:103]
	v_pk_mul_f32 v[102:103], v[138:139], v[138:139]
	v_add_f32_e32 v104, v104, v105
	v_add_f32_e32 v102, v104, v102
	v_add_f32_e32 v102, v103, v102
	v_add_f32_e32 v102, v106, v102
	s_waitcnt vmcnt(7)
	v_lshlrev_b32_e32 v140, 16, v198
	v_and_b32_e32 v141, 0xffff0000, v198
	v_pk_add_f32 v[98:99], v[98:99], v[140:141]
	v_lshlrev_b32_e32 v138, 16, v199
	v_and_b32_e32 v139, 0xffff0000, v199
	v_pk_add_f32 v[100:101], v[100:101], v[138:139]
	v_cvt_pk_bf16_f32 v138, v98, v99
	v_pk_mul_f32 v[98:99], v[98:99], v[98:99]
	v_cvt_pk_bf16_f32 v139, v100, v101
	v_pk_mul_f32 v[100:101], v[100:101], v[100:101]
	v_add_f32_e32 v98, v98, v99
	v_add_f32_e32 v98, v98, v100
	v_add_f32_e32 v98, v101, v98
	v_add_f32_e32 v98, v102, v98
	ds_swizzle_b32 v99, v98 offset:swizzle(SWAP,16)
	global_store_dwordx2 v[136:137], v[138:139], off offset:352
	s_waitcnt lgkmcnt(0)
	v_add_f32_e32 v98, v98, v99
	ds_bpermute_b32 v99, v32, v98
	s_and_saveexec_b64 s[0:1], vcc
	s_cbranch_execz .LBB0_2343
	s_waitcnt lgkmcnt(0)
	v_add_f32_e32 v100, v98, v99
	v_lshlrev_b64 v[98:99], 5, v[134:135]
	v_lshl_add_u64 v[98:99], s[10:11], 0, v[98:99]
	v_lshl_add_u64 v[98:99], s[6:7], 2, v[98:99]
	v_lshl_add_u64 v[98:99], v[130:131], 2, v[98:99]
	global_store_dword v[98:99], v100, off
; __device__ __forceinline__ uint2 pack4(float a, float b, float c, float d) { uint2 r; r.x = pk2(a, b); r.y = pk2(c, d); return r; }
;   __device__ __forceinline__ void operator()(EPI_ARGS) {
;     _Pragma("unroll") for (int bj = 0; bj < 2; ++bj) _Pragma("unroll") for (int n = 0; n < 2; ++n) {
;       int t = S_TOK(bj, n); float ss = 0.f;
;       u16* xbp = xb + (long)t * DM;
;       _Pragma("unroll") for (int ai = 0; ai < 2; ++ai) _Pragma("unroll") for (int m = 0; m < 4; ++m) {
;         int f = S_FEAT(ai, m); f32x4 a = acc[ai][bj][m][n];
;         uint2 xv = *(const uint2*)(xbp + f);
;         float v0 = __uint_as_float(xv.x << 16) + a[0], v1 = __uint_as_float(xv.x & 0xffff0000u) + a[1];
;         float v2 = __uint_as_float(xv.y << 16) + a[2], v3 = __uint_as_float(xv.y & 0xffff0000u) + a[3];
;         *(uint2*)(xbp + f) = pack4(v0, v1, v2, v3);
;         ss += v0 * v0 + v1 * v1 + v2 * v2 + v3 * v3;
;       }
;       ss += sx<16>(ss, fq * 16 + fr); ss += sx<32>(ss, fq * 16 + fr);
;       if (fq == 0) part[(long)t * 8 + (fc0 >> 8) * 2 + wr] = ss;
;     }
.LBB0_2343:
	s_or_b64 exec, exec, s[0:1]
	v_add_u32_e32 v98, 16, v134
	s_waitcnt lgkmcnt(0)
	v_ashrrev_i32_e32 v99, 31, v98
	v_lshlrev_b64 v[100:101], 11, v[98:99]
	v_lshl_add_u64 v[100:101], s[8:9], 0, v[100:101]
	v_lshl_add_u64 v[100:101], v[132:133], 1, v[100:101]
	global_load_dwordx2 v[102:103], v[100:101], off
	global_load_dwordx2 v[186:187], v[100:101], off offset:32
	global_load_dwordx2 v[188:189], v[100:101], off offset:64
	global_load_dwordx2 v[190:191], v[100:101], off offset:96
	global_load_dwordx2 v[192:193], v[100:101], off offset:256
	global_load_dwordx2 v[194:195], v[100:101], off offset:288
	global_load_dwordx2 v[196:197], v[100:101], off offset:320
	global_load_dwordx2 v[198:199], v[100:101], off offset:352
	s_waitcnt vmcnt(7)
	v_lshlrev_b32_e32 v104, 16, v102
	v_and_b32_e32 v105, 0xffff0000, v102
	v_lshlrev_b32_e32 v102, 16, v103
	v_and_b32_e32 v103, 0xffff0000, v103
	v_pk_add_f32 v[94:95], v[94:95], v[104:105]
	v_pk_add_f32 v[102:103], v[96:97], v[102:103]
	v_cvt_pk_bf16_f32 v96, v94, v95
	v_cvt_pk_bf16_f32 v97, v102, v103
	global_store_dwordx2 v[100:101], v[96:97], off
	v_pk_mul_f32 v[96:97], v[94:95], v[94:95]
	v_pk_mul_f32 v[94:95], v[102:103], v[102:103]
	s_waitcnt vmcnt(7)
	v_lshlrev_b32_e32 v104, 16, v186
	v_and_b32_e32 v105, 0xffff0000, v186
	v_lshlrev_b32_e32 v102, 16, v187
	v_and_b32_e32 v103, 0xffff0000, v187
	v_pk_add_f32 v[90:91], v[90:91], v[104:105]
	v_pk_add_f32 v[102:103], v[92:93], v[102:103]
	v_cvt_pk_bf16_f32 v92, v90, v91
	v_cvt_pk_bf16_f32 v93, v102, v103
	global_store_dwordx2 v[100:101], v[92:93], off offset:32
	v_pk_mul_f32 v[92:93], v[90:91], v[90:91]
	v_pk_mul_f32 v[90:91], v[102:103], v[102:103]
	v_add_f32_e32 v92, v92, v93
	v_add_f32_e32 v90, v92, v90
	v_add_f32_e32 v90, v91, v90
	v_add_f32_e32 v91, v96, v97
	v_add_f32_e32 v91, v91, v94
	v_add_f32_e32 v91, v95, v91
	v_add_f32_e32 v90, v91, v90
	s_waitcnt vmcnt(7)
	v_lshlrev_b32_e32 v104, 16, v188
	v_and_b32_e32 v105, 0xffff0000, v188
	v_lshlrev_b32_e32 v102, 16, v189
	v_and_b32_e32 v103, 0xffff0000, v189
	v_pk_add_f32 v[86:87], v[86:87], v[104:105]
	v_pk_add_f32 v[102:103], v[88:89], v[102:103]
	v_cvt_pk_bf16_f32 v88, v86, v87
	v_cvt_pk_bf16_f32 v89, v102, v103
	global_store_dwordx2 v[100:101], v[88:89], off offset:64
	v_pk_mul_f32 v[88:89], v[86:87], v[86:87]
	v_pk_mul_f32 v[86:87], v[102:103], v[102:103]
	v_add_f32_e32 v88, v88, v89
	v_add_f32_e32 v86, v88, v86
	v_add_f32_e32 v86, v87, v86
	v_add_f32_e32 v86, v90, v86
	s_waitcnt vmcnt(7)
	v_lshlrev_b32_e32 v104, 16, v190
	v_and_b32_e32 v105, 0xffff0000, v190
	v_lshlrev_b32_e32 v102, 16, v191
	v_and_b32_e32 v103, 0xffff0000, v191
	v_pk_add_f32 v[82:83], v[82:83], v[104:105]
	v_pk_add_f32 v[102:103], v[84:85], v[102:103]
	v_cvt_pk_bf16_f32 v84, v82, v83
	v_cvt_pk_bf16_f32 v85, v102, v103
	global_store_dwordx2 v[100:101], v[84:85], off offset:96
	v_pk_mul_f32 v[84:85], v[82:83], v[82:83]
	v_pk_mul_f32 v[82:83], v[102:103], v[102:103]
	v_add_f32_e32 v84, v84, v85
	v_add_f32_e32 v82, v84, v82
	v_add_f32_e32 v82, v83, v82
	v_add_f32_e32 v82, v86, v82
	s_waitcnt vmcnt(7)
	v_lshlrev_b32_e32 v104, 16, v192
	v_and_b32_e32 v105, 0xffff0000, v192
	v_lshlrev_b32_e32 v102, 16, v193
	v_and_b32_e32 v103, 0xffff0000, v193
	v_pk_add_f32 v[78:79], v[78:79], v[104:105]
	v_pk_add_f32 v[102:103], v[80:81], v[102:103]
	v_cvt_pk_bf16_f32 v80, v78, v79
	v_cvt_pk_bf16_f32 v81, v102, v103
	global_store_dwordx2 v[100:101], v[80:81], off offset:256
	v_pk_mul_f32 v[80:81], v[78:79], v[78:79]
	v_pk_mul_f32 v[78:79], v[102:103], v[102:103]
	v_add_f32_e32 v80, v80, v81
	v_add_f32_e32 v78, v80, v78
	v_add_f32_e32 v78, v79, v78
	v_add_f32_e32 v78, v82, v78
	s_waitcnt vmcnt(7)
	v_lshlrev_b32_e32 v104, 16, v194
	v_and_b32_e32 v105, 0xffff0000, v194
	v_lshlrev_b32_e32 v102, 16, v195
	v_and_b32_e32 v103, 0xffff0000, v195
	v_pk_add_f32 v[74:75], v[74:75], v[104:105]
	v_pk_add_f32 v[102:103], v[76:77], v[102:103]
	v_cvt_pk_bf16_f32 v76, v74, v75
	v_cvt_pk_bf16_f32 v77, v102, v103
	global_store_dwordx2 v[100:101], v[76:77], off offset:288
	v_pk_mul_f32 v[76:77], v[74:75], v[74:75]
	v_pk_mul_f32 v[74:75], v[102:103], v[102:103]
	v_add_f32_e32 v76, v76, v77
	v_add_f32_e32 v74, v76, v74
	v_add_f32_e32 v74, v75, v74
	v_add_f32_e32 v74, v78, v74
	s_waitcnt vmcnt(7)
	v_lshlrev_b32_e32 v104, 16, v196
	v_and_b32_e32 v105, 0xffff0000, v196
	v_lshlrev_b32_e32 v102, 16, v197
	v_and_b32_e32 v103, 0xffff0000, v197
	v_pk_add_f32 v[70:71], v[70:71], v[104:105]
	v_pk_add_f32 v[102:103], v[72:73], v[102:103]
	v_cvt_pk_bf16_f32 v72, v70, v71
	v_cvt_pk_bf16_f32 v73, v102, v103
	global_store_dwordx2 v[100:101], v[72:73], off offset:320
	v_pk_mul_f32 v[72:73], v[70:71], v[70:71]
	v_pk_mul_f32 v[70:71], v[102:103], v[102:103]
	v_add_f32_e32 v72, v72, v73
	v_add_f32_e32 v70, v72, v70
	v_add_f32_e32 v70, v71, v70
	v_add_f32_e32 v70, v74, v70
	s_waitcnt vmcnt(7)
	v_lshlrev_b32_e32 v104, 16, v198
	v_and_b32_e32 v105, 0xffff0000, v198
	v_pk_add_f32 v[66:67], v[66:67], v[104:105]
	v_lshlrev_b32_e32 v102, 16, v199
	v_and_b32_e32 v103, 0xffff0000, v199
	v_pk_add_f32 v[68:69], v[68:69], v[102:103]
	v_cvt_pk_bf16_f32 v102, v66, v67
	v_pk_mul_f32 v[66:67], v[66:67], v[66:67]
	v_cvt_pk_bf16_f32 v103, v68, v69
	v_pk_mul_f32 v[68:69], v[68:69], v[68:69]
	v_add_f32_e32 v66, v66, v67
	v_add_f32_e32 v66, v66, v68
	v_add_f32_e32 v66, v69, v66
	v_add_f32_e32 v66, v70, v66
	ds_swizzle_b32 v67, v66 offset:swizzle(SWAP,16)
	global_store_dwordx2 v[100:101], v[102:103], off offset:352
	s_waitcnt lgkmcnt(0)
	v_add_f32_e32 v66, v66, v67
	ds_bpermute_b32 v67, v32, v66
	s_and_saveexec_b64 s[0:1], vcc
	s_cbranch_execz .LBB0_2345
	s_waitcnt lgkmcnt(0)
	v_add_f32_e32 v68, v66, v67
	v_lshlrev_b64 v[66:67], 5, v[98:99]
	v_lshl_add_u64 v[66:67], s[10:11], 0, v[66:67]
	v_lshl_add_u64 v[66:67], s[6:7], 2, v[66:67]
	v_lshl_add_u64 v[66:67], v[130:131], 2, v[66:67]
	global_store_dword v[66:67], v68, off
; __device__ __forceinline__ uint2 pack4(float a, float b, float c, float d) { uint2 r; r.x = pk2(a, b); r.y = pk2(c, d); return r; }
;   __device__ __forceinline__ void operator()(EPI_ARGS) {
;     _Pragma("unroll") for (int bj = 0; bj < 2; ++bj) _Pragma("unroll") for (int n = 0; n < 2; ++n) {
;       int t = S_TOK(bj, n); float ss = 0.f;
;       u16* xbp = xb + (long)t * DM;
;       _Pragma("unroll") for (int ai = 0; ai < 2; ++ai) _Pragma("unroll") for (int m = 0; m < 4; ++m) {
;         int f = S_FEAT(ai, m); f32x4 a = acc[ai][bj][m][n];
;         uint2 xv = *(const uint2*)(xbp + f);
;         float v0 = __uint_as_float(xv.x << 16) + a[0], v1 = __uint_as_float(xv.x & 0xffff0000u) + a[1];
;         float v2 = __uint_as_float(xv.y << 16) + a[2], v3 = __uint_as_float(xv.y & 0xffff0000u) + a[3];
;         *(uint2*)(xbp + f) = pack4(v0, v1, v2, v3);
;         ss += v0 * v0 + v1 * v1 + v2 * v2 + v3 * v3;
;       }
;       ss += sx<16>(ss, fq * 16 + fr); ss += sx<32>(ss, fq * 16 + fr);
;       if (fq == 0) part[(long)t * 8 + (fc0 >> 8) * 2 + wr] = ss;
;     }
.LBB0_2345:
	s_or_b64 exec, exec, s[0:1]
	v_add_u32_e32 v66, 0x80, v134
	s_waitcnt lgkmcnt(0)
	v_ashrrev_i32_e32 v67, 31, v66
	v_lshlrev_b64 v[68:69], 11, v[66:67]
	v_lshl_add_u64 v[68:69], s[8:9], 0, v[68:69]
	v_lshl_add_u64 v[68:69], v[132:133], 1, v[68:69]
	global_load_dwordx2 v[70:71], v[68:69], off
	global_load_dwordx2 v[186:187], v[68:69], off offset:32
	global_load_dwordx2 v[188:189], v[68:69], off offset:64
	global_load_dwordx2 v[190:191], v[68:69], off offset:96
	global_load_dwordx2 v[192:193], v[68:69], off offset:256
	global_load_dwordx2 v[194:195], v[68:69], off offset:288
	global_load_dwordx2 v[196:197], v[68:69], off offset:320
	global_load_dwordx2 v[198:199], v[68:69], off offset:352
	s_waitcnt vmcnt(7)
	v_lshlrev_b32_e32 v72, 16, v70
	v_and_b32_e32 v73, 0xffff0000, v70
	v_lshlrev_b32_e32 v70, 16, v71
	v_and_b32_e32 v71, 0xffff0000, v71
	v_pk_add_f32 v[62:63], v[62:63], v[72:73]
	v_pk_add_f32 v[70:71], v[64:65], v[70:71]
	v_cvt_pk_bf16_f32 v64, v62, v63
	v_cvt_pk_bf16_f32 v65, v70, v71
	global_store_dwordx2 v[68:69], v[64:65], off
	v_pk_mul_f32 v[64:65], v[62:63], v[62:63]
	v_pk_mul_f32 v[62:63], v[70:71], v[70:71]
	s_waitcnt vmcnt(7)
	v_lshlrev_b32_e32 v72, 16, v186
	v_and_b32_e32 v73, 0xffff0000, v186
	v_lshlrev_b32_e32 v70, 16, v187
	v_and_b32_e32 v71, 0xffff0000, v187
	v_pk_add_f32 v[58:59], v[58:59], v[72:73]
	v_pk_add_f32 v[70:71], v[60:61], v[70:71]
	v_cvt_pk_bf16_f32 v60, v58, v59
	v_cvt_pk_bf16_f32 v61, v70, v71
	global_store_dwordx2 v[68:69], v[60:61], off offset:32
	v_pk_mul_f32 v[60:61], v[58:59], v[58:59]
	v_pk_mul_f32 v[58:59], v[70:71], v[70:71]
	v_add_f32_e32 v60, v60, v61
	v_add_f32_e32 v58, v60, v58
	v_add_f32_e32 v58, v59, v58
	v_add_f32_e32 v59, v64, v65
	v_add_f32_e32 v59, v59, v62
	v_add_f32_e32 v59, v63, v59
	v_add_f32_e32 v58, v59, v58
	s_waitcnt vmcnt(7)
	v_lshlrev_b32_e32 v72, 16, v188
	v_and_b32_e32 v73, 0xffff0000, v188
	v_lshlrev_b32_e32 v70, 16, v189
	v_and_b32_e32 v71, 0xffff0000, v189
	v_pk_add_f32 v[54:55], v[54:55], v[72:73]
	v_pk_add_f32 v[70:71], v[56:57], v[70:71]
	v_cvt_pk_bf16_f32 v56, v54, v55
	v_cvt_pk_bf16_f32 v57, v70, v71
	global_store_dwordx2 v[68:69], v[56:57], off offset:64
	v_pk_mul_f32 v[56:57], v[54:55], v[54:55]
	v_pk_mul_f32 v[54:55], v[70:71], v[70:71]
	v_add_f32_e32 v56, v56, v57
	v_add_f32_e32 v54, v56, v54
	v_add_f32_e32 v54, v55, v54
	v_add_f32_e32 v54, v58, v54
	s_waitcnt vmcnt(7)
	v_lshlrev_b32_e32 v72, 16, v190
	v_and_b32_e32 v73, 0xffff0000, v190
	v_lshlrev_b32_e32 v70, 16, v191
	v_and_b32_e32 v71, 0xffff0000, v191
	v_pk_add_f32 v[50:51], v[50:51], v[72:73]
	v_pk_add_f32 v[70:71], v[52:53], v[70:71]
	v_cvt_pk_bf16_f32 v52, v50, v51
	v_cvt_pk_bf16_f32 v53, v70, v71
	global_store_dwordx2 v[68:69], v[52:53], off offset:96
	v_pk_mul_f32 v[52:53], v[50:51], v[50:51]
	v_pk_mul_f32 v[50:51], v[70:71], v[70:71]
	v_add_f32_e32 v52, v52, v53
	v_add_f32_e32 v50, v52, v50
	v_add_f32_e32 v50, v51, v50
	v_add_f32_e32 v50, v54, v50
	s_waitcnt vmcnt(7)
	v_lshlrev_b32_e32 v72, 16, v192
	v_and_b32_e32 v73, 0xffff0000, v192
	v_lshlrev_b32_e32 v70, 16, v193
	v_and_b32_e32 v71, 0xffff0000, v193
	v_pk_add_f32 v[46:47], v[46:47], v[72:73]
	v_pk_add_f32 v[70:71], v[48:49], v[70:71]
	v_cvt_pk_bf16_f32 v48, v46, v47
	v_cvt_pk_bf16_f32 v49, v70, v71
	global_store_dwordx2 v[68:69], v[48:49], off offset:256
	v_pk_mul_f32 v[48:49], v[46:47], v[46:47]
	v_pk_mul_f32 v[46:47], v[70:71], v[70:71]
	v_add_f32_e32 v48, v48, v49
	v_add_f32_e32 v46, v48, v46
	v_add_f32_e32 v46, v47, v46
	v_add_f32_e32 v46, v50, v46
	s_waitcnt vmcnt(7)
	v_lshlrev_b32_e32 v72, 16, v194
	v_and_b32_e32 v73, 0xffff0000, v194
	v_lshlrev_b32_e32 v70, 16, v195
	v_and_b32_e32 v71, 0xffff0000, v195
	v_pk_add_f32 v[42:43], v[42:43], v[72:73]
	v_pk_add_f32 v[70:71], v[44:45], v[70:71]
	v_cvt_pk_bf16_f32 v44, v42, v43
	v_cvt_pk_bf16_f32 v45, v70, v71
	global_store_dwordx2 v[68:69], v[44:45], off offset:288
	v_pk_mul_f32 v[44:45], v[42:43], v[42:43]
	v_pk_mul_f32 v[42:43], v[70:71], v[70:71]
	v_add_f32_e32 v44, v44, v45
	v_add_f32_e32 v42, v44, v42
	v_add_f32_e32 v42, v43, v42
	v_add_f32_e32 v42, v46, v42
	s_waitcnt vmcnt(7)
	v_lshlrev_b32_e32 v72, 16, v196
	v_and_b32_e32 v73, 0xffff0000, v196
	v_lshlrev_b32_e32 v70, 16, v197
	v_and_b32_e32 v71, 0xffff0000, v197
	v_pk_add_f32 v[38:39], v[38:39], v[72:73]
	v_pk_add_f32 v[70:71], v[40:41], v[70:71]
	v_cvt_pk_bf16_f32 v40, v38, v39
	v_cvt_pk_bf16_f32 v41, v70, v71
	global_store_dwordx2 v[68:69], v[40:41], off offset:320
	v_pk_mul_f32 v[40:41], v[38:39], v[38:39]
	v_pk_mul_f32 v[38:39], v[70:71], v[70:71]
	v_add_f32_e32 v40, v40, v41
	v_add_f32_e32 v38, v40, v38
	v_add_f32_e32 v38, v39, v38
	v_add_f32_e32 v38, v42, v38
	s_waitcnt vmcnt(7)
	v_lshlrev_b32_e32 v72, 16, v198
	v_and_b32_e32 v73, 0xffff0000, v198
	v_pk_add_f32 v[34:35], v[34:35], v[72:73]
	v_lshlrev_b32_e32 v70, 16, v199
	v_and_b32_e32 v71, 0xffff0000, v199
	v_pk_add_f32 v[36:37], v[36:37], v[70:71]
	v_cvt_pk_bf16_f32 v70, v34, v35
	v_pk_mul_f32 v[34:35], v[34:35], v[34:35]
	v_cvt_pk_bf16_f32 v71, v36, v37
	v_pk_mul_f32 v[36:37], v[36:37], v[36:37]
	v_add_f32_e32 v34, v34, v35
	v_add_f32_e32 v34, v34, v36
	v_add_f32_e32 v34, v37, v34
	v_add_f32_e32 v34, v38, v34
	ds_swizzle_b32 v35, v34 offset:swizzle(SWAP,16)
	global_store_dwordx2 v[68:69], v[70:71], off offset:352
	s_waitcnt lgkmcnt(0)
	v_add_f32_e32 v34, v34, v35
	ds_bpermute_b32 v35, v32, v34
	s_and_saveexec_b64 s[0:1], vcc
	s_cbranch_execz .LBB0_2347
	s_waitcnt lgkmcnt(0)
	v_add_f32_e32 v36, v34, v35
	v_lshlrev_b64 v[34:35], 5, v[66:67]
	v_lshl_add_u64 v[34:35], s[10:11], 0, v[34:35]
	v_lshl_add_u64 v[34:35], s[6:7], 2, v[34:35]
	v_lshl_add_u64 v[34:35], v[130:131], 2, v[34:35]
	global_store_dword v[34:35], v36, off
; __device__ __forceinline__ uint2 pack4(float a, float b, float c, float d) { uint2 r; r.x = pk2(a, b); r.y = pk2(c, d); return r; }
;   __device__ __forceinline__ void operator()(EPI_ARGS) {
;     _Pragma("unroll") for (int bj = 0; bj < 2; ++bj) _Pragma("unroll") for (int n = 0; n < 2; ++n) {
;       int t = S_TOK(bj, n); float ss = 0.f;
;       u16* xbp = xb + (long)t * DM;
;       _Pragma("unroll") for (int ai = 0; ai < 2; ++ai) _Pragma("unroll") for (int m = 0; m < 4; ++m) {
;         int f = S_FEAT(ai, m); f32x4 a = acc[ai][bj][m][n];
;         uint2 xv = *(const uint2*)(xbp + f);
;         float v0 = __uint_as_float(xv.x << 16) + a[0], v1 = __uint_as_float(xv.x & 0xffff0000u) + a[1];
;         float v2 = __uint_as_float(xv.y << 16) + a[2], v3 = __uint_as_float(xv.y & 0xffff0000u) + a[3];
;         *(uint2*)(xbp + f) = pack4(v0, v1, v2, v3);
;         ss += v0 * v0 + v1 * v1 + v2 * v2 + v3 * v3;
;       }
;       ss += sx<16>(ss, fq * 16 + fr); ss += sx<32>(ss, fq * 16 + fr);
;       if (fq == 0) part[(long)t * 8 + (fc0 >> 8) * 2 + wr] = ss;
;     }
.LBB0_2347:
	s_or_b64 exec, exec, s[0:1]
	v_add_u32_e32 v34, 0x90, v134
	s_waitcnt lgkmcnt(0)
	v_ashrrev_i32_e32 v35, 31, v34
	v_lshlrev_b64 v[36:37], 11, v[34:35]
	v_lshl_add_u64 v[36:37], s[8:9], 0, v[36:37]
	v_lshl_add_u64 v[36:37], v[132:133], 1, v[36:37]
	global_load_dwordx2 v[38:39], v[36:37], off
	global_load_dwordx2 v[186:187], v[36:37], off offset:32
	global_load_dwordx2 v[188:189], v[36:37], off offset:64
	global_load_dwordx2 v[190:191], v[36:37], off offset:96
	global_load_dwordx2 v[192:193], v[36:37], off offset:256
	global_load_dwordx2 v[194:195], v[36:37], off offset:288
	global_load_dwordx2 v[196:197], v[36:37], off offset:320
	global_load_dwordx2 v[198:199], v[36:37], off offset:352
	s_waitcnt vmcnt(7)
	v_lshlrev_b32_e32 v40, 16, v38
	v_and_b32_e32 v41, 0xffff0000, v38
	v_lshlrev_b32_e32 v38, 16, v39
	v_and_b32_e32 v39, 0xffff0000, v39
	v_pk_add_f32 v[28:29], v[28:29], v[40:41]
	v_pk_add_f32 v[38:39], v[30:31], v[38:39]
	v_cvt_pk_bf16_f32 v30, v28, v29
	v_cvt_pk_bf16_f32 v31, v38, v39
	global_store_dwordx2 v[36:37], v[30:31], off
	v_pk_mul_f32 v[30:31], v[28:29], v[28:29]
	v_pk_mul_f32 v[28:29], v[38:39], v[38:39]
	s_waitcnt vmcnt(7)
	v_lshlrev_b32_e32 v40, 16, v186
	v_and_b32_e32 v41, 0xffff0000, v186
	v_lshlrev_b32_e32 v38, 16, v187
	v_and_b32_e32 v39, 0xffff0000, v187
	v_pk_add_f32 v[24:25], v[24:25], v[40:41]
	v_pk_add_f32 v[38:39], v[26:27], v[38:39]
	v_cvt_pk_bf16_f32 v26, v24, v25
	v_cvt_pk_bf16_f32 v27, v38, v39
	global_store_dwordx2 v[36:37], v[26:27], off offset:32
	v_pk_mul_f32 v[26:27], v[24:25], v[24:25]
	v_pk_mul_f32 v[24:25], v[38:39], v[38:39]
	v_add_f32_e32 v26, v26, v27
	v_add_f32_e32 v24, v26, v24
	v_add_f32_e32 v24, v25, v24
	v_add_f32_e32 v25, v30, v31
	v_add_f32_e32 v25, v25, v28
	v_add_f32_e32 v25, v29, v25
	v_add_f32_e32 v24, v25, v24
	s_waitcnt vmcnt(7)
	v_lshlrev_b32_e32 v40, 16, v188
	v_and_b32_e32 v41, 0xffff0000, v188
	v_lshlrev_b32_e32 v38, 16, v189
	v_and_b32_e32 v39, 0xffff0000, v189
	v_pk_add_f32 v[20:21], v[20:21], v[40:41]
	v_pk_add_f32 v[38:39], v[22:23], v[38:39]
	v_cvt_pk_bf16_f32 v22, v20, v21
	v_cvt_pk_bf16_f32 v23, v38, v39
	global_store_dwordx2 v[36:37], v[22:23], off offset:64
	v_pk_mul_f32 v[22:23], v[20:21], v[20:21]
	v_pk_mul_f32 v[20:21], v[38:39], v[38:39]
	v_add_f32_e32 v22, v22, v23
	v_add_f32_e32 v20, v22, v20
	v_add_f32_e32 v20, v21, v20
	v_add_f32_e32 v20, v24, v20
	s_waitcnt vmcnt(7)
	v_lshlrev_b32_e32 v40, 16, v190
	v_and_b32_e32 v41, 0xffff0000, v190
	v_lshlrev_b32_e32 v38, 16, v191
	v_and_b32_e32 v39, 0xffff0000, v191
	v_pk_add_f32 v[16:17], v[16:17], v[40:41]
	v_pk_add_f32 v[38:39], v[18:19], v[38:39]
	v_cvt_pk_bf16_f32 v18, v16, v17
	v_cvt_pk_bf16_f32 v19, v38, v39
	global_store_dwordx2 v[36:37], v[18:19], off offset:96
	v_pk_mul_f32 v[18:19], v[16:17], v[16:17]
	v_pk_mul_f32 v[16:17], v[38:39], v[38:39]
	v_add_f32_e32 v18, v18, v19
	v_add_f32_e32 v16, v18, v16
	v_add_f32_e32 v16, v17, v16
	v_add_f32_e32 v16, v20, v16
	s_waitcnt vmcnt(7)
	v_lshlrev_b32_e32 v40, 16, v192
	v_and_b32_e32 v41, 0xffff0000, v192
	v_lshlrev_b32_e32 v38, 16, v193
	v_and_b32_e32 v39, 0xffff0000, v193
	v_pk_add_f32 v[12:13], v[12:13], v[40:41]
	v_pk_add_f32 v[38:39], v[14:15], v[38:39]
	v_cvt_pk_bf16_f32 v14, v12, v13
	v_cvt_pk_bf16_f32 v15, v38, v39
	global_store_dwordx2 v[36:37], v[14:15], off offset:256
	v_pk_mul_f32 v[14:15], v[12:13], v[12:13]
	v_pk_mul_f32 v[12:13], v[38:39], v[38:39]
	v_add_f32_e32 v14, v14, v15
	v_add_f32_e32 v12, v14, v12
	v_add_f32_e32 v12, v13, v12
	v_add_f32_e32 v12, v16, v12
	s_waitcnt vmcnt(7)
	v_lshlrev_b32_e32 v40, 16, v194
	v_and_b32_e32 v41, 0xffff0000, v194
	v_lshlrev_b32_e32 v38, 16, v195
	v_and_b32_e32 v39, 0xffff0000, v195
	v_pk_add_f32 v[8:9], v[8:9], v[40:41]
	v_pk_add_f32 v[38:39], v[10:11], v[38:39]
	v_cvt_pk_bf16_f32 v10, v8, v9
	v_cvt_pk_bf16_f32 v11, v38, v39
	global_store_dwordx2 v[36:37], v[10:11], off offset:288
	v_pk_mul_f32 v[10:11], v[8:9], v[8:9]
	v_pk_mul_f32 v[8:9], v[38:39], v[38:39]
	v_add_f32_e32 v10, v10, v11
	v_add_f32_e32 v8, v10, v8
	v_add_f32_e32 v8, v9, v8
	v_add_f32_e32 v8, v12, v8
	s_waitcnt vmcnt(7)
	v_lshlrev_b32_e32 v40, 16, v196
	v_and_b32_e32 v41, 0xffff0000, v196
	v_lshlrev_b32_e32 v38, 16, v197
	v_and_b32_e32 v39, 0xffff0000, v197
	v_pk_add_f32 v[4:5], v[4:5], v[40:41]
	v_pk_add_f32 v[38:39], v[6:7], v[38:39]
	v_cvt_pk_bf16_f32 v6, v4, v5
	v_cvt_pk_bf16_f32 v7, v38, v39
	global_store_dwordx2 v[36:37], v[6:7], off offset:320
	v_pk_mul_f32 v[6:7], v[4:5], v[4:5]
	v_pk_mul_f32 v[4:5], v[38:39], v[38:39]
	v_add_f32_e32 v6, v6, v7
	v_add_f32_e32 v4, v6, v4
	v_add_f32_e32 v4, v5, v4
	v_add_f32_e32 v4, v8, v4
	s_waitcnt vmcnt(7)
	v_lshlrev_b32_e32 v40, 16, v198
	v_and_b32_e32 v41, 0xffff0000, v198
	v_pk_add_f32 v[0:1], v[0:1], v[40:41]
	v_lshlrev_b32_e32 v38, 16, v199
	v_and_b32_e32 v39, 0xffff0000, v199
	v_pk_add_f32 v[2:3], v[2:3], v[38:39]
	v_cvt_pk_bf16_f32 v38, v0, v1
	v_pk_mul_f32 v[0:1], v[0:1], v[0:1]
	v_cvt_pk_bf16_f32 v39, v2, v3
	v_pk_mul_f32 v[2:3], v[2:3], v[2:3]
	v_add_f32_e32 v0, v0, v1
	v_add_f32_e32 v0, v0, v2
	v_add_f32_e32 v0, v3, v0
	v_add_f32_e32 v0, v4, v0
	ds_swizzle_b32 v1, v0 offset:swizzle(SWAP,16)
	global_store_dwordx2 v[36:37], v[38:39], off offset:352
	s_waitcnt lgkmcnt(0)
	v_add_f32_e32 v0, v0, v1
	ds_bpermute_b32 v1, v32, v0
	s_and_saveexec_b64 s[0:1], vcc
	s_cbranch_execz .LBB0_2320
	s_waitcnt lgkmcnt(0)
	v_add_f32_e32 v2, v0, v1
	v_lshlrev_b64 v[0:1], 5, v[34:35]
	v_lshl_add_u64 v[0:1], s[10:11], 0, v[0:1]
	v_lshl_add_u64 v[0:1], s[6:7], 2, v[0:1]
	v_lshl_add_u64 v[0:1], v[130:131], 2, v[0:1]
	global_store_dword v[0:1], v2, off
	s_branch .LBB0_2320
